# NA and GQA attention loops: the per-element bias/mask LUT reads (32 and 16 serial ds_read+wait+add blocks under exec masks) batched with up to 15 reads in flight and v_cndmask selects
# speedup vs baseline: 1.0287x; 1.0257x over previous
; #define LAS __attribute__((address_space(3)))
; #define SBAR_() __builtin_amdgcn_sched_barrier(0)
; template <int MODE, bool FROZEN = false>
; __device__ __forceinline__ bool attn_unit(LAS unsigned char* lds, const Params& p, int l, int ua, int ub) {
;     ...
;         {
;             const size_t advk = (size_t)min(t + 3, NT - 1) * 64 * NPROJ, advv = (size_t)min(t + 2, NT - 1) * 64;
; #pragma unroll
;             for (int i = 0; i < NKC; ++i) kr[i] = *(const u32x4*)(kvbase + advk + ksrc[i]);
; #pragma unroll
;             for (int i = 0; i < NVC; ++i) vr[i] = *(const u32x4*)(vtbase + advv + vsrc[i]);
;         }
;         f32x16 sA0 = sB0, sA1 = sB1;
;         const float c2 = cbB - m_run;
;         const LAS unsigned char* Vb = lds + OFF_V + (t & 1) * VBUF + vlane_off;
;         const LAS unsigned char* Kb = lds + OFF_K + ((t + 1) & 1) * KBUF + klane_off;
;     ...
;         bf16x8 kf0[4], kf1[4], va[NB], vb[NB], pf0, pf1; float ps0, ps1, ps2, ps3;
;         VLOAD(0, va);
;         EXPCVT(0, pf0, ps0);
;         SBAR_();
;         VLOAD(1, vb); PVMMA(va, pf0); EXPCVT(1, pf1, ps1); _Pragma("unroll") for (int g_ = 0; g_ < NB; ++g_) { __builtin_amdgcn_sched_group_barrier(0x008, 1, 0); __builtin_amdgcn_sched_group_barrier(0x100, 1, 0); __builtin_amdgcn_sched_group_barrier(0x400, 8 / NB, 0); __builtin_amdgcn_sched_group_barrier(0x002, 12 / NB, 0); } SBAR_();
;         VLOAD(2, va);
; #pragma unroll
;         for (int d0 = 0; d0 < 4; ++d0) { kf0[d0] = *(const LAS bf16x8*)(Kb + d0 * 32); kf1[d0] = *(const LAS bf16x8*)(Kb + 32 * KPB + d0 * 32); }
;         PVMMA(vb, pf1); EXPCVT(2, pf0, ps2); _Pragma("unroll") for (int g_ = 0; g_ < NB; ++g_) { __builtin_amdgcn_sched_group_barrier(0x008, 1, 0); __builtin_amdgcn_sched_group_barrier(0x100, 1, 0); __builtin_amdgcn_sched_group_barrier(0x400, 8 / NB, 0); __builtin_amdgcn_sched_group_barrier(0x002, 12 / NB, 0); } SBAR_();
;         {
;             f32x16 z0, z1;
; #pragma unroll
;             for (int r = 0; r < 16; ++r) { z0[r] = 0.f; z1[r] = 0.f; }
; #pragma unroll
;             for (int d0 = 0; d0 < 4; ++d0) { z0 = __builtin_amdgcn_mfma_f32_32x32x16_bf16(kf0[d0], qf[d0], z0, 0, 0, 0); z1 = __builtin_amdgcn_mfma_f32_32x32x16_bf16(kf1[d0], qf[d0], z1, 0, 0, 0); }
;             sB0 = z0; sB1 = z1;
;         }
;         EXPCVT(3, pf1, ps3);
; #pragma unroll
.LBB0_264:
	s_add_i32 s12, s21, 3
	s_min_i32 vcc_lo, s12, s18
	s_min_i32 s12, s23, s18
	s_ashr_i32 s13, s12, 31
	s_lshl_b64 s[12:13], s[12:13], 7
	v_mad_i64_i32 v[68:69], vcc, vcc_lo, v243, v[126:127]
	v_lshl_add_u64 v[70:71], v[128:129], 0, s[12:13]
	global_load_dwordx4 v[120:123], v[68:69], off
	global_load_dwordx4 v[116:119], v[70:71], off
	v_add_f32_e64 v35, -v152, v52
	v_exp_f32_e32 v84, v35
	v_add_f32_e64 v35, -v152, v53
	v_exp_f32_e32 v86, v35
	v_add_f32_e64 v35, -v152, v54
	v_exp_f32_e32 v138, v35
	v_add_f32_e64 v35, -v152, v55
	v_exp_f32_e32 v142, v35
	v_add_f32_e64 v35, -v152, v56
	v_exp_f32_e32 v134, v35
	v_add_f32_e64 v35, -v152, v57
	s_bitcmp1_b32 s21, 0
	v_exp_f32_e32 v140, v35
	v_add_f32_e64 v35, -v152, v58
	s_cselect_b32 s12, 0x2400, 0
	v_exp_f32_e32 v132, v35
	v_add_f32_e64 v35, -v152, v59
	v_add_u32_e32 v1, s12, v150
	v_exp_f32_e32 v136, v35
	ds_read_b128 v[68:71], v1 offset:18432
	ds_read_b128 v[72:75], v1 offset:23040
	v_cvt_pk_bf16_f32 v52, v84, v86
	v_cvt_pk_bf16_f32 v53, v138, v142
	v_cvt_pk_bf16_f32 v54, v134, v140
	v_cvt_pk_bf16_f32 v55, v132, v136
	s_waitcnt lgkmcnt(1)
	s_nop 0
	v_mfma_f32_32x32x16_bf16 v[2:17], v[68:71], v[52:55], v[2:17]
	ds_read_b128 v[56:59], v1 offset:18464
	v_add_f32_e64 v60, -v152, v60
	v_exp_f32_e32 v98, v60
	v_add_f32_e64 v61, -v152, v61
	v_exp_f32_e32 v96, v61
	v_add_f32_e64 v62, -v152, v62
	v_exp_f32_e32 v146, v62
	v_add_f32_e64 v35, -v152, v64
	v_exp_f32_e32 v90, v35
	v_add_f32_e64 v35, -v152, v65
	v_exp_f32_e32 v94, v35
	v_add_f32_e64 v35, -v152, v66
	v_exp_f32_e32 v88, v35
	v_add_f32_e64 v35, -v152, v67
	v_exp_f32_e32 v92, v35
	v_add_f32_e64 v35, -v152, v63
	v_exp_f32_e32 v144, v35
	v_cvt_pk_bf16_f32 v62, v90, v94
	v_cvt_pk_bf16_f32 v63, v88, v92
	v_cvt_pk_bf16_f32 v61, v146, v144
	s_waitcnt lgkmcnt(1)
	v_mfma_f32_32x32x16_bf16 v[18:33], v[72:75], v[52:55], v[18:33]
	ds_read_b128 v[52:55], v1 offset:23072
	v_cvt_pk_bf16_f32 v60, v98, v96
	v_add_u32_e32 v35, s22, v149
	s_waitcnt lgkmcnt(1)
	v_mfma_f32_32x32x16_bf16 v[2:17], v[56:59], v[60:63], v[2:17]
	ds_read_b128 v[72:75], v1 offset:18496
	v_add_f32_e64 v36, -v152, v36
	v_exp_f32_e32 v85, v36
	v_add_f32_e64 v36, -v152, v43
	v_exp_f32_e32 v137, v36
	v_add_f32_e64 v37, -v152, v37
	v_exp_f32_e32 v87, v37
	v_add_f32_e64 v37, -v152, v42
	v_exp_f32_e32 v133, v37
	v_add_f32_e64 v38, -v152, v38
	v_exp_f32_e32 v139, v38
	v_add_f32_e64 v38, -v152, v41
	v_exp_f32_e32 v141, v38
	v_add_f32_e64 v39, -v152, v39
	v_exp_f32_e32 v143, v39
	v_add_f32_e64 v39, -v152, v40
	v_exp_f32_e32 v135, v39
	v_cvt_pk_bf16_f32 v83, v133, v137
	ds_read_b128 v[36:39], v35 offset:4608
	ds_read_b128 v[56:59], v35 offset:4640
	v_cvt_pk_bf16_f32 v82, v135, v141
	s_waitcnt lgkmcnt(3)
	v_mfma_f32_32x32x16_bf16 v[18:33], v[52:55], v[60:63], v[18:33]
	ds_read_b128 v[52:55], v35
	ds_read_b128 v[60:63], v35 offset:4672
	ds_read_b128 v[64:67], v35 offset:4704
	ds_read_b128 v[68:71], v1 offset:23104
	ds_read_b128 v[154:157], v35 offset:32
	ds_read_b128 v[158:161], v35 offset:64
	ds_read_b128 v[162:165], v35 offset:96
	v_cvt_pk_bf16_f32 v80, v85, v87
	v_cvt_pk_bf16_f32 v81, v139, v143
	v_add_f32_e64 v35, -v152, v51
	v_exp_f32_e32 v93, v35
	v_add_f32_e64 v35, -v152, v44
	v_exp_f32_e32 v99, v35
	v_add_f32_e64 v35, -v152, v46
	v_exp_f32_e32 v147, v35
	v_add_f32_e64 v35, -v152, v50
	v_exp_f32_e32 v89, v35
	v_add_f32_e64 v40, -v152, v45
	v_add_f32_e64 v76, -v152, v47
	v_add_f32_e64 v78, -v152, v48
	v_exp_f32_e32 v97, v40
	v_add_f32_e64 v79, -v152, v49
	s_waitcnt lgkmcnt(8)
	v_mfma_f32_32x32x16_bf16 v[36:51], v[36:39], v[100:103], 0
	s_waitcnt lgkmcnt(7)
	v_mfma_f32_32x32x16_bf16 v[36:51], v[56:59], v[104:107], v[36:51]
	s_waitcnt lgkmcnt(5)
	v_mfma_f32_32x32x16_bf16 v[36:51], v[60:63], v[108:111], v[36:51]
	s_waitcnt lgkmcnt(4)
	v_mfma_f32_32x32x16_bf16 v[36:51], v[64:67], v[112:115], v[36:51]
	v_mfma_f32_32x32x16_bf16 v[52:67], v[52:55], v[100:103], 0
	s_waitcnt lgkmcnt(2)
	v_mfma_f32_32x32x16_bf16 v[52:67], v[154:157], v[104:107], v[52:67]
	s_waitcnt lgkmcnt(1)
	v_mfma_f32_32x32x16_bf16 v[52:67], v[158:161], v[108:111], v[52:67]
	v_exp_f32_e32 v145, v76
	v_cvt_pk_bf16_f32 v76, v99, v97
	v_cvt_pk_bf16_f32 v77, v147, v145
	v_exp_f32_e32 v91, v78
	v_exp_f32_e32 v95, v79
	s_waitcnt lgkmcnt(0)
	v_mfma_f32_32x32x16_bf16 v[52:67], v[162:165], v[112:115], v[52:67]
	v_cvt_pk_bf16_f32 v79, v89, v93
	v_cvt_pk_bf16_f32 v78, v91, v95
	ds_read_b128 v[154:157], v1 offset:18528
	ds_read_b128 v[158:161], v1 offset:23136
	v_mfma_f32_32x32x16_bf16 v[2:17], v[72:75], v[80:83], v[2:17]
	v_add_f32_e64 v72, v138, v142
	v_add_f32_e64 v73, v139, v143
	v_add_f32_e64 v74, v134, v140
	v_add_f32_e64 v75, v135, v141
	v_add_f32_e64 v132, v132, v136
	v_add_f32_e64 v133, v133, v137
	v_pk_add_f32 v[84:85], v[84:85], v[86:87]
	v_pk_add_f32 v[74:75], v[74:75], v[132:133]
	s_andn2_b64 vcc, exec, s[10:11]
	v_mfma_f32_32x32x16_bf16 v[18:33], v[68:71], v[80:83], v[18:33]
	v_add_f32_e64 v68, v84, v72
	v_add_f32_e64 v69, v85, v73
	v_add_f32_e64 v72, v90, v94
	v_add_f32_e64 v73, v91, v95
	v_add_f32_e64 v68, v68, v74
	v_add_f32_e64 v69, v69, v75
	v_pk_add_f32 v[74:75], v[88:89], v[92:93]
	v_pk_add_f32 v[70:71], v[146:147], v[144:145]
	v_pk_add_f32 v[72:73], v[72:73], v[74:75]
	v_pk_add_f32 v[74:75], v[98:99], v[96:97]
	s_waitcnt lgkmcnt(1)
	v_mfma_f32_32x32x16_bf16 v[2:17], v[154:157], v[76:79], v[2:17]
	v_add_f32_e64 v70, v74, v70
	v_add_f32_e64 v71, v75, v71
	v_add_f32_e64 v70, v70, v72
	v_add_f32_e64 v71, v71, v73
	v_add_f32_e64 v68, v68, v70
	v_add_f32_e64 v69, v69, v71
	v_add_f32_e32 v1, v68, v69
	s_waitcnt lgkmcnt(0)
	v_mfma_f32_32x32x16_bf16 v[18:33], v[158:161], v[76:79], v[18:33]
	v_add_f32_e32 v0, v0, v1
	s_cbranch_vccnz .LBB0_334
	s_cmp_lt_i32 s20, s16
	s_cselect_b64 s[10:11], -1, 0
	s_cmp_ge_i32 s21, s8
	s_cselect_b64 s[12:13], -1, 0
	s_or_b64 s[10:11], s[12:13], s[10:11]
	s_and_b64 vcc, exec, s[10:11]
	s_cbranch_vccnz .LBB0_331
	s_add_i32 s10, s19, s21
	s_max_i32 s10, s10, -7
	s_add_i32 s10, s10, 7
	s_min_u32 s10, s10, 14
	s_mulk_i32 s10, 0x1fc
	v_add_u32_e32 v1, s10, v151
	v_mov_b32_e32 v35, 0xf149f2ca
	ds_read_b32 v68, v1 offset:36864
	ds_read_b32 v69, v1 offset:36992
	ds_read_b32 v70, v1 offset:36868
	ds_read_b32 v71, v1 offset:36996
	ds_read_b32 v72, v1 offset:36872
	ds_read_b32 v73, v1 offset:37000
	ds_read_b32 v74, v1 offset:36876
	ds_read_b32 v75, v1 offset:37004
	ds_read_b32 v76, v1 offset:36896
	ds_read_b32 v77, v1 offset:37024
	ds_read_b32 v78, v1 offset:36900
	ds_read_b32 v79, v1 offset:37028
	ds_read_b32 v80, v1 offset:36904
	ds_read_b32 v81, v1 offset:37032
	ds_read_b32 v82, v1 offset:36908
	s_waitcnt lgkmcnt(14)
	v_add_f32_e32 v68, v52, v68
	ds_read_b32 v83, v1 offset:37036
	v_cndmask_b32_e64 v52, v35, v68, s[38:39]
	s_waitcnt lgkmcnt(14)
	v_add_f32_e32 v69, v36, v69
	ds_read_b32 v84, v1 offset:36928
	v_cndmask_b32_e64 v36, v35, v69, s[40:41]
	s_waitcnt lgkmcnt(14)
	v_add_f32_e32 v70, v53, v70
	ds_read_b32 v85, v1 offset:37056
	v_cndmask_b32_e64 v53, v35, v70, s[42:43]
	s_waitcnt lgkmcnt(14)
	v_add_f32_e32 v71, v37, v71
	ds_read_b32 v86, v1 offset:36932
	v_cndmask_b32_e64 v37, v35, v71, s[44:45]
	s_waitcnt lgkmcnt(14)
	v_add_f32_e32 v72, v54, v72
	ds_read_b32 v87, v1 offset:37060
	v_cndmask_b32_e64 v54, v35, v72, s[46:47]
	s_waitcnt lgkmcnt(14)
	v_add_f32_e32 v73, v38, v73
	ds_read_b32 v88, v1 offset:36936
	v_cndmask_b32_e64 v38, v35, v73, s[48:49]
	s_waitcnt lgkmcnt(14)
	v_add_f32_e32 v74, v55, v74
	ds_read_b32 v89, v1 offset:37064
	v_cndmask_b32_e64 v55, v35, v74, s[50:51]
	s_waitcnt lgkmcnt(14)
	v_add_f32_e32 v75, v39, v75
	ds_read_b32 v90, v1 offset:36940
	v_cndmask_b32_e64 v39, v35, v75, s[52:53]
	s_waitcnt lgkmcnt(14)
	v_add_f32_e32 v76, v56, v76
	ds_read_b32 v91, v1 offset:37068
	v_cndmask_b32_e64 v56, v35, v76, s[54:55]
	s_waitcnt lgkmcnt(14)
	v_add_f32_e32 v77, v40, v77
	ds_read_b32 v92, v1 offset:36960
	v_cndmask_b32_e64 v40, v35, v77, s[56:57]
	s_waitcnt lgkmcnt(14)
	v_add_f32_e32 v78, v57, v78
	ds_read_b32 v93, v1 offset:37088
	v_cndmask_b32_e64 v57, v35, v78, s[58:59]
	s_waitcnt lgkmcnt(14)
	v_add_f32_e32 v79, v41, v79
	ds_read_b32 v94, v1 offset:36964
	v_cndmask_b32_e64 v41, v35, v79, s[60:61]
	s_waitcnt lgkmcnt(14)
	v_add_f32_e32 v80, v58, v80
	ds_read_b32 v95, v1 offset:37092
	v_cndmask_b32_e64 v58, v35, v80, s[62:63]
	s_waitcnt lgkmcnt(14)
	v_add_f32_e32 v81, v42, v81
	ds_read_b32 v96, v1 offset:36968
	v_cndmask_b32_e64 v42, v35, v81, s[64:65]
	s_waitcnt lgkmcnt(14)
	v_add_f32_e32 v82, v59, v82
	ds_read_b32 v97, v1 offset:37096
	v_cndmask_b32_e64 v59, v35, v82, s[66:67]
	s_waitcnt lgkmcnt(14)
	v_add_f32_e32 v83, v43, v83
	ds_read_b32 v98, v1 offset:36972
	v_cndmask_b32_e64 v43, v35, v83, s[68:69]
	s_waitcnt lgkmcnt(14)
	v_add_f32_e32 v84, v60, v84
	ds_read_b32 v99, v1 offset:37100
	v_cndmask_b32_e64 v60, v35, v84, s[70:71]
	s_waitcnt lgkmcnt(14)
	v_add_f32_e32 v85, v44, v85
	v_cndmask_b32_e64 v44, v35, v85, s[72:73]
	s_waitcnt lgkmcnt(13)
	v_add_f32_e32 v86, v61, v86
	v_cndmask_b32_e64 v61, v35, v86, s[74:75]
	s_waitcnt lgkmcnt(12)
	v_add_f32_e32 v87, v45, v87
	v_cndmask_b32_e64 v45, v35, v87, s[76:77]
	s_waitcnt lgkmcnt(11)
	v_add_f32_e32 v88, v62, v88
	v_cndmask_b32_e64 v62, v35, v88, s[78:79]
	s_waitcnt lgkmcnt(10)
	v_add_f32_e32 v89, v46, v89
	v_cndmask_b32_e64 v46, v35, v89, s[80:81]
	s_waitcnt lgkmcnt(9)
	v_add_f32_e32 v90, v63, v90
	v_cndmask_b32_e64 v63, v35, v90, s[82:83]
	s_waitcnt lgkmcnt(8)
	v_add_f32_e32 v91, v47, v91
	v_cndmask_b32_e64 v47, v35, v91, s[84:85]
	s_waitcnt lgkmcnt(7)
	v_add_f32_e32 v92, v64, v92
	v_cndmask_b32_e64 v64, v35, v92, s[86:87]
	s_waitcnt lgkmcnt(6)
	v_add_f32_e32 v93, v48, v93
	v_cndmask_b32_e64 v48, v35, v93, s[88:89]
	s_waitcnt lgkmcnt(5)
	v_add_f32_e32 v94, v65, v94
	v_cndmask_b32_e64 v65, v35, v94, s[90:91]
	s_waitcnt lgkmcnt(4)
	v_add_f32_e32 v95, v49, v95
	v_cndmask_b32_e64 v49, v35, v95, s[92:93]
	s_waitcnt lgkmcnt(3)
	v_add_f32_e32 v96, v66, v96
	v_cndmask_b32_e64 v66, v35, v96, s[94:95]
	s_waitcnt lgkmcnt(2)
	v_add_f32_e32 v97, v50, v97
	v_cndmask_b32_e64 v50, v35, v97, s[96:97]
	s_waitcnt lgkmcnt(1)
	v_add_f32_e32 v98, v67, v98
	v_cndmask_b32_e64 v67, v35, v98, s[0:1]
	s_waitcnt lgkmcnt(0)
	v_add_f32_e32 v99, v51, v99
	v_cndmask_b32_e64 v51, v35, v99, s[4:5]
	s_branch .LBB0_332

; #define LAS __attribute__((address_space(3)))
; #define SBAR_() __builtin_amdgcn_sched_barrier(0)
; template <int MODE, bool FROZEN = false>
; __device__ __forceinline__ bool attn_unit(LAS unsigned char* lds, const Params& p, int l, int ua, int ub) {
;     ...
;         {
;             const size_t advk = (size_t)min(t + 3, NT - 1) * 64 * NPROJ, advv = (size_t)min(t + 2, NT - 1) * 64;
; #pragma unroll
;             for (int i = 0; i < NKC; ++i) kr[i] = *(const u32x4*)(kvbase + advk + ksrc[i]);
; #pragma unroll
;             for (int i = 0; i < NVC; ++i) vr[i] = *(const u32x4*)(vtbase + advv + vsrc[i]);
;         }
;         f32x16 sA0 = sB0, sA1 = sB1;
;         const float c2 = cbB - m_run;
;         const LAS unsigned char* Vb = lds + OFF_V + (t & 1) * VBUF + vlane_off;
;         const LAS unsigned char* Kb = lds + OFF_K + ((t + 1) & 1) * KBUF + klane_off;
;     ...
;         bf16x8 kf0[4], kf1[4], va[NB], vb[NB], pf0, pf1; float ps0, ps1, ps2, ps3;
;         VLOAD(0, va);
;         EXPCVT(0, pf0, ps0);
;         SBAR_();
;         VLOAD(1, vb); PVMMA(va, pf0); EXPCVT(1, pf1, ps1); _Pragma("unroll") for (int g_ = 0; g_ < NB; ++g_) { __builtin_amdgcn_sched_group_barrier(0x008, 1, 0); __builtin_amdgcn_sched_group_barrier(0x100, 1, 0); __builtin_amdgcn_sched_group_barrier(0x400, 8 / NB, 0); __builtin_amdgcn_sched_group_barrier(0x002, 12 / NB, 0); } SBAR_();
;         VLOAD(2, va);
; #pragma unroll
;         for (int d0 = 0; d0 < 4; ++d0) { kf0[d0] = *(const LAS bf16x8*)(Kb + d0 * 32); kf1[d0] = *(const LAS bf16x8*)(Kb + 32 * KPB + d0 * 32); }
;         PVMMA(vb, pf1); EXPCVT(2, pf0, ps2); _Pragma("unroll") for (int g_ = 0; g_ < NB; ++g_) { __builtin_amdgcn_sched_group_barrier(0x008, 1, 0); __builtin_amdgcn_sched_group_barrier(0x100, 1, 0); __builtin_amdgcn_sched_group_barrier(0x400, 8 / NB, 0); __builtin_amdgcn_sched_group_barrier(0x002, 12 / NB, 0); } SBAR_();
;         {
;             f32x16 z0, z1;
; #pragma unroll
;             for (int r = 0; r < 16; ++r) { z0[r] = 0.f; z1[r] = 0.f; }
; #pragma unroll
;             for (int d0 = 0; d0 < 4; ++d0) { z0 = __builtin_amdgcn_mfma_f32_32x32x16_bf16(kf0[d0], qf[d0], z0, 0, 0, 0); z1 = __builtin_amdgcn_mfma_f32_32x32x16_bf16(kf1[d0], qf[d0], z1, 0, 0, 0); }
;             sB0 = z0; sB1 = z1;
;         }
;         EXPCVT(3, pf1, ps3);
; #pragma unroll
.LBB0_510:
	s_add_i32 s10, s15, 3
	s_min_i32 s10, s10, s12
	s_min_i32 s8, s8, s12
	s_waitcnt vmcnt(0)
	v_mad_u64_u32 v[84:85], s[10:11], s10, v243, v[108:109]
	s_lshl_b64 s[10:11], s[8:9], 7
	s_nop 0
	v_lshl_add_u64 v[86:87], v[110:111], 0, s[10:11]
	global_load_dwordx4 v[88:91], v[84:85], off
	v_add_f32_e64 v16, -v149, v16
	global_load_dwordx4 v[84:87], v[86:87], off
	v_exp_f32_e32 v112, v16
	v_add_f32_e64 v16, -v149, v17
	v_exp_f32_e32 v114, v16
	v_add_f32_e64 v16, -v149, v18
	v_exp_f32_e32 v134, v16
	v_add_f32_e64 v16, -v149, v19
	v_exp_f32_e32 v138, v16
	v_add_f32_e64 v16, -v149, v20
	v_exp_f32_e32 v130, v16
	v_add_f32_e64 v16, -v149, v21
	s_bitcmp1_b32 s15, 0
	v_exp_f32_e32 v136, v16
	v_add_f32_e64 v16, -v149, v22
	s_cselect_b32 s8, 0x2400, 0
	v_exp_f32_e32 v128, v16
	v_add_f32_e64 v16, -v149, v23
	v_add_u32_e32 v150, s8, v147
	v_exp_f32_e32 v132, v16
	ds_read_b128 v[92:95], v150 offset:18432
	ds_read_b128 v[96:99], v150 offset:23040
	v_cvt_pk_bf16_f32 v16, v112, v114
	v_cvt_pk_bf16_f32 v17, v134, v138
	v_cvt_pk_bf16_f32 v18, v130, v136
	v_cvt_pk_bf16_f32 v19, v128, v132
	s_waitcnt lgkmcnt(1)
	s_nop 0
	v_mfma_f32_32x32x16_bf16 v[52:67], v[92:95], v[16:19], v[52:67]
	ds_read_b128 v[20:23], v150 offset:18464
	v_add_f32_e64 v24, -v149, v24
	v_exp_f32_e32 v126, v24
	v_add_f32_e64 v25, -v149, v25
	v_exp_f32_e32 v124, v25
	v_add_f32_e64 v26, -v149, v26
	v_exp_f32_e32 v142, v26
	v_add_f32_e64 v27, -v149, v27
	v_exp_f32_e32 v140, v27
	v_add_f32_e64 v28, -v149, v28
	v_cvt_pk_bf16_f32 v24, v126, v124
	s_waitcnt lgkmcnt(1)
	v_mfma_f32_32x32x16_bf16 v[36:51], v[96:99], v[16:19], v[36:51]
	ds_read_b128 v[16:19], v150 offset:23072
	v_exp_f32_e32 v118, v28
	v_add_f32_e64 v28, -v149, v29
	v_exp_f32_e32 v122, v28
	v_add_f32_e64 v28, -v149, v30
	v_exp_f32_e32 v116, v28
	v_add_f32_e64 v28, -v149, v31
	v_exp_f32_e32 v120, v28
	v_add_u32_e32 v28, s16, v145
	v_cvt_pk_bf16_f32 v25, v142, v140
	v_cvt_pk_bf16_f32 v26, v118, v122
	v_cvt_pk_bf16_f32 v27, v116, v120
	s_waitcnt lgkmcnt(1)
	s_nop 0
	v_mfma_f32_32x32x16_bf16 v[52:67], v[20:23], v[24:27], v[52:67]
	ds_read_b128 v[96:99], v150 offset:18496
	v_add_f32_e64 v0, -v149, v0
	v_exp_f32_e32 v113, v0
	v_add_f32_e64 v0, -v149, v7
	v_exp_f32_e32 v133, v0
	v_add_f32_e64 v1, -v149, v1
	v_exp_f32_e32 v115, v1
	v_add_f32_e64 v1, -v149, v6
	v_exp_f32_e32 v129, v1
	v_add_f32_e64 v2, -v149, v2
	v_exp_f32_e32 v135, v2
	v_add_f32_e64 v2, -v149, v5
	v_exp_f32_e32 v137, v2
	v_add_f32_e64 v3, -v149, v3
	v_exp_f32_e32 v139, v3
	v_add_f32_e64 v3, -v149, v4
	v_exp_f32_e32 v131, v3
	v_cvt_pk_bf16_f32 v107, v129, v133
	ds_read_b128 v[0:3], v28 offset:4608
	ds_read_b128 v[152:155], v28 offset:32
	v_cvt_pk_bf16_f32 v106, v131, v137
	s_waitcnt lgkmcnt(3)
	v_mfma_f32_32x32x16_bf16 v[36:51], v[16:19], v[24:27], v[36:51]
	ds_read_b128 v[16:19], v28
	ds_read_b128 v[20:23], v28 offset:4640
	ds_read_b128 v[156:159], v28 offset:64
	ds_read_b128 v[24:27], v28 offset:4672
	ds_read_b128 v[160:163], v28 offset:96
	ds_read_b128 v[28:31], v28 offset:4704
	ds_read_b128 v[92:95], v150 offset:23104
	v_cvt_pk_bf16_f32 v104, v113, v115
	v_cvt_pk_bf16_f32 v105, v135, v139
	v_add_f32_e64 v117, -v149, v14
	v_exp_f32_e32 v117, v117
	v_add_f32_e64 v4, -v149, v15
	v_add_f32_e64 v5, -v149, v9
	v_exp_f32_e32 v121, v4
	v_add_f32_e64 v4, -v149, v8
	v_add_f32_e64 v100, -v149, v11
	v_exp_f32_e32 v127, v4
	v_add_f32_e64 v4, -v149, v10
	v_add_f32_e64 v102, -v149, v12
	v_exp_f32_e32 v125, v5
	v_add_f32_e64 v103, -v149, v13
	v_exp_f32_e32 v143, v4
	s_waitcnt lgkmcnt(8)
	v_mfma_f32_32x32x16_bf16 v[0:15], v[0:3], v[68:71], 0
	s_waitcnt lgkmcnt(5)
	v_mfma_f32_32x32x16_bf16 v[0:15], v[20:23], v[72:75], v[0:15]
	s_waitcnt lgkmcnt(3)
	v_mfma_f32_32x32x16_bf16 v[0:15], v[24:27], v[76:79], v[0:15]
	s_waitcnt lgkmcnt(1)
	v_mfma_f32_32x32x16_bf16 v[0:15], v[28:31], v[80:83], v[0:15]
	v_mfma_f32_32x32x16_bf16 v[16:31], v[16:19], v[68:71], 0
	v_mfma_f32_32x32x16_bf16 v[16:31], v[152:155], v[72:75], v[16:31]
	v_mfma_f32_32x32x16_bf16 v[16:31], v[156:159], v[76:79], v[16:31]
	v_exp_f32_e32 v141, v100
	v_cvt_pk_bf16_f32 v100, v127, v125
	v_cvt_pk_bf16_f32 v101, v143, v141
	v_exp_f32_e32 v119, v102
	v_exp_f32_e32 v123, v103
	v_mfma_f32_32x32x16_bf16 v[16:31], v[160:163], v[80:83], v[16:31]
	v_cvt_pk_bf16_f32 v103, v117, v121
	v_cvt_pk_bf16_f32 v102, v119, v123
	ds_read_b128 v[152:155], v150 offset:18528
	ds_read_b128 v[156:159], v150 offset:23136
	v_mfma_f32_32x32x16_bf16 v[52:67], v[96:99], v[104:107], v[52:67]
	v_add_f32_e64 v96, v134, v138
	v_add_f32_e64 v97, v135, v139
	v_add_f32_e64 v98, v130, v136
	v_add_f32_e64 v99, v131, v137
	v_add_f32_e64 v128, v128, v132
	v_add_f32_e64 v129, v129, v133
	v_pk_add_f32 v[112:113], v[112:113], v[114:115]
	v_pk_add_f32 v[98:99], v[98:99], v[128:129]
	s_andn2_b64 vcc, exec, s[0:1]
	s_waitcnt lgkmcnt(2)
	v_mfma_f32_32x32x16_bf16 v[36:51], v[92:95], v[104:107], v[36:51]
	v_add_f32_e64 v92, v112, v96
	v_add_f32_e64 v93, v113, v97
	v_add_f32_e64 v96, v118, v122
	v_add_f32_e64 v97, v119, v123
	v_add_f32_e64 v92, v92, v98
	v_add_f32_e64 v93, v93, v99
	v_pk_add_f32 v[98:99], v[116:117], v[120:121]
	v_pk_add_f32 v[94:95], v[142:143], v[140:141]
	v_pk_add_f32 v[96:97], v[96:97], v[98:99]
	v_pk_add_f32 v[98:99], v[126:127], v[124:125]
	s_waitcnt lgkmcnt(1)
	v_mfma_f32_32x32x16_bf16 v[52:67], v[152:155], v[100:103], v[52:67]
	v_add_f32_e64 v94, v98, v94
	v_add_f32_e64 v95, v99, v95
	v_add_f32_e64 v94, v94, v96
	v_add_f32_e64 v95, v95, v97
	v_add_f32_e64 v92, v92, v94
	v_add_f32_e64 v93, v93, v95
	v_add_f32_e32 v92, v92, v93
	s_waitcnt lgkmcnt(0)
	v_mfma_f32_32x32x16_bf16 v[36:51], v[156:159], v[100:103], v[36:51]
	v_add_f32_e32 v146, v146, v92
	s_cbranch_vccnz .LBB0_513
	ds_read2_b32 v[112:113], v148 offset1:1
	ds_read2_b32 v[114:115], v148 offset0:2 offset1:3
	ds_read2_b32 v[116:117], v148 offset0:8 offset1:9
	ds_read2_b32 v[118:119], v148 offset0:10 offset1:11
	ds_read2_b32 v[120:121], v148 offset0:16 offset1:17
	ds_read2_b32 v[122:123], v148 offset0:18 offset1:19
	ds_read2_b32 v[124:125], v148 offset0:24 offset1:25
	ds_read2_b32 v[126:127], v148 offset0:26 offset1:27
	ds_read2_b32 v[128:129], v148 offset0:32 offset1:33
	ds_read2_b32 v[130:131], v148 offset0:34 offset1:35
	ds_read2_b32 v[132:133], v148 offset0:40 offset1:41
	ds_read2_b32 v[134:135], v148 offset0:42 offset1:43
	ds_read2_b32 v[136:137], v148 offset0:48 offset1:49
	ds_read2_b32 v[138:139], v148 offset0:50 offset1:51
	ds_read2_b32 v[140:141], v148 offset0:56 offset1:57
	s_waitcnt lgkmcnt(14)
	v_pk_add_f32 v[112:113], v[112:113], 0 op_sel_hi:[1,0]
	ds_read2_b32 v[142:143], v148 offset0:58 offset1:59
	v_pk_add_f32 v[16:17], v[16:17], v[112:113]
	s_waitcnt lgkmcnt(14)
	v_pk_add_f32 v[114:115], v[114:115], 0 op_sel_hi:[1,0]
	s_nop 0
	v_pk_add_f32 v[18:19], v[18:19], v[114:115]
	s_waitcnt lgkmcnt(13)
	v_pk_add_f32 v[116:117], v[116:117], 0 op_sel_hi:[1,0]
	s_nop 0
	v_pk_add_f32 v[20:21], v[20:21], v[116:117]
	s_waitcnt lgkmcnt(12)
	v_pk_add_f32 v[118:119], v[118:119], 0 op_sel_hi:[1,0]
	s_nop 0
	v_pk_add_f32 v[22:23], v[22:23], v[118:119]
	s_waitcnt lgkmcnt(11)
	v_pk_add_f32 v[120:121], v[120:121], 0 op_sel_hi:[1,0]
	s_nop 0
	v_pk_add_f32 v[24:25], v[24:25], v[120:121]
	s_waitcnt lgkmcnt(10)
	v_pk_add_f32 v[122:123], v[122:123], 0 op_sel_hi:[1,0]
	s_nop 0
	v_pk_add_f32 v[26:27], v[26:27], v[122:123]
	s_waitcnt lgkmcnt(9)
	v_pk_add_f32 v[124:125], v[124:125], 0 op_sel_hi:[1,0]
	s_nop 0
	v_pk_add_f32 v[28:29], v[28:29], v[124:125]
	s_waitcnt lgkmcnt(8)
	v_pk_add_f32 v[126:127], v[126:127], 0 op_sel_hi:[1,0]
	s_nop 0
	v_pk_add_f32 v[30:31], v[30:31], v[126:127]
	s_waitcnt lgkmcnt(7)
	v_pk_add_f32 v[128:129], v[128:129], 0 op_sel_hi:[1,0]
	s_nop 0
	v_pk_add_f32 v[0:1], v[0:1], v[128:129]
	s_waitcnt lgkmcnt(6)
	v_pk_add_f32 v[130:131], v[130:131], 0 op_sel_hi:[1,0]
	s_nop 0
	v_pk_add_f32 v[2:3], v[2:3], v[130:131]
	s_waitcnt lgkmcnt(5)
	v_pk_add_f32 v[132:133], v[132:133], 0 op_sel_hi:[1,0]
	s_nop 0
	v_pk_add_f32 v[4:5], v[4:5], v[132:133]
	s_waitcnt lgkmcnt(4)
	v_pk_add_f32 v[134:135], v[134:135], 0 op_sel_hi:[1,0]
	s_nop 0
	v_pk_add_f32 v[6:7], v[6:7], v[134:135]
	s_waitcnt lgkmcnt(3)
	v_pk_add_f32 v[136:137], v[136:137], 0 op_sel_hi:[1,0]
	s_nop 0
	v_pk_add_f32 v[8:9], v[8:9], v[136:137]
	s_waitcnt lgkmcnt(2)
	v_pk_add_f32 v[138:139], v[138:139], 0 op_sel_hi:[1,0]
	s_nop 0
	v_pk_add_f32 v[10:11], v[10:11], v[138:139]
	s_waitcnt lgkmcnt(1)
	v_pk_add_f32 v[140:141], v[140:141], 0 op_sel_hi:[1,0]
	s_nop 0
	v_pk_add_f32 v[12:13], v[12:13], v[140:141]
	s_waitcnt lgkmcnt(0)
	v_pk_add_f32 v[142:143], v[142:143], 0 op_sel_hi:[1,0]
	s_nop 0
	v_pk_add_f32 v[14:15], v[14:15], v[142:143]
	v_max_f32_e32 v92, v16, v0
	v_max3_f32 v93, v1, v18, v2
	v_max3_f32 v92, v92, v17, v19
	v_max3_f32 v93, v93, v20, v4
	v_max3_f32 v92, v92, v3, v21
	v_max3_f32 v93, v93, v22, v6
	v_max3_f32 v92, v92, v5, v23
	v_max3_f32 v93, v93, v24, v8
	v_max3_f32 v92, v92, v7, v25
	v_max3_f32 v93, v93, v26, v10
	v_max3_f32 v92, v92, v9, v27
	v_max3_f32 v93, v93, v28, v12
	v_max3_f32 v92, v92, v11, v29
	v_max3_f32 v93, v93, v30, v14
	v_max3_f32 v92, v92, v13, v31
	v_max3_f32 v92, v92, v15, v93
	v_mov_b32_e32 v93, v92
	s_nop 1
	v_permlane32_swap_b32_e32 v92, v93
	v_max_f32_e32 v93, v93, v93
	v_max_f32_e32 v92, v92, v92
	v_max_f32_e32 v92, v92, v93
	v_cmp_gt_f32_e32 vcc, v92, v149
	s_cbranch_vccz .LBB0_513
	v_add_f32_e32 v92, 0, v92
	v_max_f32_e32 v93, v149, v149
	v_max_f32_e32 v93, v93, v92
	v_sub_f32_e32 v92, v149, v93
	v_exp_f32_e32 v92, v92
	v_mov_b32_e32 v149, v93
	v_pk_mul_f32 v[50:51], v[50:51], v[92:93] op_sel_hi:[1,0]
	v_pk_mul_f32 v[48:49], v[48:49], v[92:93] op_sel_hi:[1,0]
	v_pk_mul_f32 v[46:47], v[46:47], v[92:93] op_sel_hi:[1,0]
	v_pk_mul_f32 v[44:45], v[44:45], v[92:93] op_sel_hi:[1,0]
	v_pk_mul_f32 v[42:43], v[42:43], v[92:93] op_sel_hi:[1,0]
	v_pk_mul_f32 v[40:41], v[40:41], v[92:93] op_sel_hi:[1,0]
	v_pk_mul_f32 v[38:39], v[38:39], v[92:93] op_sel_hi:[1,0]
	v_pk_mul_f32 v[36:37], v[36:37], v[92:93] op_sel_hi:[1,0]
	v_pk_mul_f32 v[66:67], v[66:67], v[92:93] op_sel_hi:[1,0]
	v_pk_mul_f32 v[64:65], v[64:65], v[92:93] op_sel_hi:[1,0]
	v_pk_mul_f32 v[62:63], v[62:63], v[92:93] op_sel_hi:[1,0]
	v_pk_mul_f32 v[60:61], v[60:61], v[92:93] op_sel_hi:[1,0]
	v_pk_mul_f32 v[58:59], v[58:59], v[92:93] op_sel_hi:[1,0]
	v_pk_mul_f32 v[56:57], v[56:57], v[92:93] op_sel_hi:[1,0]
	v_pk_mul_f32 v[54:55], v[54:55], v[92:93] op_sel_hi:[1,0]
	v_pk_mul_f32 v[52:53], v[52:53], v[92:93] op_sel_hi:[1,0]
	v_mul_f32_e32 v146, v146, v92
